# merge phase: workgroups 176..255 (no sample-row split-K unit afterwards) start 6 us late so that their gate-load epilogues fall into the others' K-loops
# baseline (speedup 1.0000x reference)
; __device__ __forceinline__ int lane_id_v() { int l; asm volatile("v_mbcnt_lo_u32_b32 %0, -1, 0\n\tv_mbcnt_hi_u32_b32 %0, -1, %0" : "=v"(l)); return l; }
;         const int tile = vc + (i / 3) * G; if (tile >= 256) return false; const int br = i % 3; u.pm = br * 66 + (tile >> 2); u.pn = br * 4 + (tile & 3); u.k0 = 0; return true; }
; __global__ void __launch_bounds__(512, 2) mega(Args a_unused) {
;     ...
;                 { pg8::Gemm g{(const bf16_t*)(ws + WS_DYY), (const bf16_t*)(ws + WS_WBR) + (size_t)l * 3072 * 512, 3 * M, 3072, 512, 0, 0}; pg8::BranchOrder S{G, c};
;                   pg8::EpiMerge E{(const bf16_t*)(ws + WS_GT), (float*)(ws + WS_XA), H};
;                   pg8::gemm_phase<pg8::EpiMerge, pg8::BranchOrder, true, true>(lds, g, S, E, wave_s * 64 + lane_id_v()); }
.LBB0_281:
	s_and_b64 vcc, exec, s[2:3]
	s_cbranch_vccz .LBB0_447
	s_cmpk_lt_i32 s38, 0xb0
	s_cbranch_scc1 .Lmd_nosleep
	s_sleep 127
	s_sleep 64
.Lmd_nosleep:
	s_and_b32 s2, s51, 7
	v_mbcnt_lo_u32_b32 v0, -1, 0
	v_mbcnt_hi_u32_b32 v0, -1, v0
	s_cmp_eq_u32 s2, 0
	v_add_u32_e32 v14, s90, v0
	s_cselect_b64 s[10:11], -1, 0
	v_readfirstlane_b32 s8, v14
	s_cmp_lg_u32 s2, 0
	s_mov_b32 s4, s38
	s_cbranch_scc1 .LBB0_284
	s_ashr_i32 s3, s38, 31
	s_lshr_b32 s3, s3, 29
	s_add_i32 s3, s38, s3
	s_and_b32 s4, s3, -8
	s_ashr_i32 s2, s51, 3
	s_sub_i32 s4, s38, s4
	s_mul_i32 s2, s4, s2
	s_ashr_i32 s3, s3, 3
	s_add_i32 s4, s2, s3
